# prompt stick-breaking steps after the diagonal one run a hand-written unmasked body (no causal-mask selects)
# baseline (speedup 1.0000x reference)
; #define LDS_AS __attribute__((address_space(3)))
; DI void prompt_sb_unit(const Params& p, int b, int h, int qt, char* smem) {
;     int tid_ = threadIdx.x; asm volatile("" : "+v"(tid_));
;     const int tid = tid_, lane = tid & 63, wave = tid >> 6, l31 = lane & 31, hh = lane >> 5;
;     LDS_AS char* lb = (LDS_AS char*)smem + wave * 9216;
;     const int wq0 = qt * 256 + 32 * wave, qpos = wq0 + l31;
;     const int qcol = h * 64, kcol = qcol + 512, vcol = qcol + 1024, gcol = qcol + 1536;
;     const size_t rowb = (size_t)b * LPAD;
;     __syncthreads();
;     if (wq0 < LP) {
;         bf16x8 q[4];
;         {
;             const bf16_t* qp = p.u + (rowb + qpos) * NU + qcol + 8 * hh;
; #pragma unroll
;             for (int s = 0; s < 4; ++s) q[s] = *(const bf16x8*)(qp + 16 * s);
;         }
;         AttnState st;
; #pragma unroll
;         for (int i = 0; i < 16; ++i) { st.o0[i] = 0.f; st.o1[i] = 0.f; }
;         st.m = -1e30f; st.l = 0.f;
;         u32x4 rk[4], rv[4];
;         const int r0 = lane >> 3, c0 = lane & 7;
;         const bf16_t* ub = p.u + (rowb + r0) * NU + c0 * 8;
;         int kp = wq0;
;         {
;             const bf16_t* kb = ub + (size_t)kp * NU;
; #pragma unroll
;             for (int i = 0; i < 4; ++i) { rk[i] = *(const u32x4*)(kb + (size_t)(8 * i) * NU + kcol); rv[i] = *(const u32x4*)(kb + (size_t)(8 * i) * NU + vcol); }
;         }
;         for (;;) {
;             asm volatile("s_waitcnt lgkmcnt(0)" ::: "memory");
; #pragma unroll
;             for (int i = 0; i < 4; ++i) { *(LDS_AS u32x4*)(lb + (r0 + 8 * i) * 144 + c0 * 16) = rk[i]; *(LDS_AS u32x4*)(lb + 4608 + (r0 + 8 * i) * 144 + c0 * 16) = rv[i]; }
;             const int kn = kp - 32;
;             if (kn >= 0) {
;                 const bf16_t* kb = ub + (size_t)kn * NU;
; #pragma unroll
;                 for (int i = 0; i < 4; ++i) { rk[i] = *(const u32x4*)(kb + (size_t)(8 * i) * NU + kcol); rv[i] = *(const u32x4*)(kb + (size_t)(8 * i) * NU + vcol); }
;             }
.LBB0_424:
	s_or_b64 exec, exec, s[0:1]
	v_mov_b32_e32 v0, s63
	s_waitcnt lgkmcnt(0)
	s_barrier
	ds_read_b32 v0, v0
	s_mov_b64 s[0:1], -1
	s_waitcnt lgkmcnt(0)
	v_cmp_lt_i32_e32 vcc, s66, v0
	v_readfirstlane_b32 s4, v0
	s_cbranch_vccnz .LBB0_419
	v_mov_b32_e32 v3, v138
	s_lshl_b32 s0, s4, 3
	v_ashrrev_i32_e32 v4, 6, v3
	s_and_b32 s0, s0, 0xffffff00
	v_lshlrev_b32_e32 v2, 5, v4
	s_waitcnt vmcnt(13)
	v_subrev_u32_e32 v104, s0, v2
	v_add_u32_e32 v0, 0x1000, v104
	v_cmp_gt_i32_e32 vcc, s88, v0
	s_barrier
	s_and_saveexec_b64 s[6:7], vcc
	s_cbranch_execz .LBB0_418
	v_and_b32_e32 v5, 31, v3
	v_or_b32_e32 v98, v0, v5
	s_bfe_u32 s1, s4, 0x20003
	s_mul_i32 s10, s1, 0x1040
	v_ashrrev_i32_e32 v99, 31, v98
	s_lshl_b32 s1, s4, 6
	v_lshl_add_u64 v[96:97], v[98:99], 0, s[10:11]
	s_and_b32 s39, s1, 0x1c0
	v_lshlrev_b64 v[6:7], 13, v[96:97]
	v_bfe_u32 v12, v3, 5, 1
	v_lshl_add_u64 v[6:7], s[68:69], 0, v[6:7]
	s_lshl_b32 s4, s39, 1
	s_mov_b32 s5, s11
	v_lshl_add_u64 v[100:101], v[6:7], 0, s[4:5]
	v_lshlrev_b32_e32 v130, 4, v12
	v_bfe_u32 v13, v3, 3, 3
	v_lshl_add_u64 v[6:7], v[100:101], 0, v[130:131]
	v_or_b32_e32 v1, s10, v13
	global_load_dwordx4 v[48:51], v[6:7], off
	global_load_dwordx4 v[52:55], v[6:7], off offset:32
	global_load_dwordx4 v[56:59], v[6:7], off offset:64
	global_load_dwordx4 v[60:63], v[6:7], off offset:96
	v_lshlrev_b32_e32 v6, 13, v1
	v_mov_b32_e32 v7, v131
	v_lshlrev_b32_e32 v1, 4, v3
	v_lshl_add_u64 v[6:7], s[68:69], 0, v[6:7]
	v_and_b32_e32 v8, 0x70, v1
	v_mov_b32_e32 v9, v131
	v_ashrrev_i32_e32 v1, 31, v0
	v_lshl_add_u64 v[102:103], v[6:7], 0, v[8:9]
	v_lshlrev_b64 v[0:1], 13, v[0:1]
	v_lshl_add_u64 v[0:1], v[102:103], 0, v[0:1]
	s_or_b32 s1, s39, 0x400
	s_or_b32 s30, s39, 0x200
	v_lshl_add_u64 v[6:7], v[0:1], 0, s[4:5]
	global_load_dwordx4 v[64:67], v[6:7], off offset:1024
	global_load_dwordx4 v[68:71], v[6:7], off offset:2048
	v_lshl_add_u64 v[6:7], v[0:1], 0, s[14:15]
	s_lshl_b32 s10, s30, 1
	s_lshl_b32 s4, s1, 1
	v_lshl_add_u64 v[10:11], v[6:7], 0, s[10:11]
	v_lshl_add_u64 v[6:7], v[6:7], 0, s[4:5]
	global_load_dwordx4 v[72:75], v[10:11], off
	global_load_dwordx4 v[76:79], v[6:7], off
	v_lshl_add_u64 v[6:7], v[0:1], 0, s[16:17]
	v_lshl_add_u64 v[10:11], v[6:7], 0, s[10:11]
	v_lshl_add_u64 v[6:7], v[6:7], 0, s[4:5]
	v_lshl_add_u64 v[0:1], v[0:1], 0, s[20:21]
	global_load_dwordx4 v[80:83], v[10:11], off
	global_load_dwordx4 v[84:87], v[6:7], off
	v_lshl_add_u64 v[6:7], v[0:1], 0, s[10:11]
	v_lshl_add_u64 v[0:1], v[0:1], 0, s[4:5]
	global_load_dwordx4 v[88:91], v[6:7], off
	global_load_dwordx4 v[92:95], v[0:1], off
	s_movk_i32 s4, 0x2400
	v_and_b32_e32 v1, 63, v3
	v_mul_lo_u32 v0, v4, s4
	v_lshlrev_b32_e32 v99, 2, v12
	v_cmp_gt_u32_e32 vcc, 32, v1
	v_lshrrev_b32_e32 v1, 2, v3
	v_and_b32_e32 v6, 16, v3
	v_lshlrev_b32_e32 v3, 2, v3
	v_add_u32_e32 v0, 0x100, v0
	v_and_or_b32 v1, v1, 3, v99
	v_and_or_b32 v3, v3, 12, v6
	v_add_u32_e32 v4, v0, v8
	v_mad_u32_u24 v5, v5, s89, v0
	v_mad_u32_u24 v0, v1, s89, v0
	v_lshlrev_b32_e32 v1, 1, v3
	v_mul_u32_u24_e32 v3, 0x90, v13
	v_add_u32_e32 v2, v2, v99
	v_mov_b32_e32 v106, 0
	v_subrev_u32_e32 v105, s0, v2
	s_mov_b32 s42, 0
	s_mov_b64 s[8:9], 0
	v_add_u32_e32 v107, v4, v3
	s_lshl_b32 s30, s30, 1
	s_lshl_b32 s34, s1, 1
	s_waitcnt vmcnt(24)
	v_add_u32_e32 v108, v5, v130
	v_add_u32_e32 v109, v0, v1
	v_mov_b32_e32 v0, 0
	v_mov_b32_e32 v1, v106
	v_mov_b32_e32 v2, v106
	v_mov_b32_e32 v3, v106
	v_mov_b32_e32 v4, v106
	v_mov_b32_e32 v5, v106
	v_mov_b32_e32 v6, v106
	v_mov_b32_e32 v7, v106
	v_mov_b32_e32 v8, v106
	v_mov_b32_e32 v9, v106
	v_mov_b32_e32 v10, v106
	v_mov_b32_e32 v11, v106
	v_mov_b32_e32 v12, v106
	v_mov_b32_e32 v13, v106
	v_mov_b32_e32 v14, v106
	v_mov_b32_e32 v15, v106
	v_mov_b32_e32 v16, 0
	v_mov_b32_e32 v17, v106
	v_mov_b32_e32 v18, v106
	v_mov_b32_e32 v19, v106
	v_mov_b32_e32 v20, v106
	v_mov_b32_e32 v21, v106
	v_mov_b32_e32 v22, v106
	v_mov_b32_e32 v23, v106
	v_mov_b32_e32 v24, v106
	v_mov_b32_e32 v25, v106
	v_mov_b32_e32 v26, v106
	v_mov_b32_e32 v27, v106
	v_mov_b32_e32 v28, v106
	v_mov_b32_e32 v29, v106
	v_mov_b32_e32 v30, v106
	v_mov_b32_e32 v31, v106
	s_branch .LBB0_428
.Lsbl_body:
	v_add_u32_e32 v32, s42, v104
	s_waitcnt lgkmcnt(0)
	v_add_u32_e32 v110, 0x1000, v32
	v_cmp_lt_i32_e64 s[0:1], 31, v110
	s_waitcnt vmcnt(7)
	ds_write_b128 v107, v[64:67]
	s_waitcnt vmcnt(6)
	ds_write_b128 v107, v[68:71] offset:4608
	s_waitcnt vmcnt(5)
	ds_write_b128 v107, v[72:75] offset:1152
	s_waitcnt vmcnt(4)
	ds_write_b128 v107, v[76:79] offset:5760
	s_waitcnt vmcnt(3)
	ds_write_b128 v107, v[80:83] offset:2304
	s_waitcnt vmcnt(2)
	ds_write_b128 v107, v[84:87] offset:6912
	s_waitcnt vmcnt(1)
	ds_write_b128 v107, v[88:91] offset:3456
	s_waitcnt vmcnt(0)
	ds_write_b128 v107, v[92:95] offset:8064
	s_and_saveexec_b64 s[4:5], s[0:1]
	s_cbranch_execz .Lsbl_430
	v_add_u32_e32 v130, 0xfe0, v32
	v_lshlrev_b64 v[32:33], 13, v[130:131]
	v_lshl_add_u64 v[32:33], v[102:103], 0, v[32:33]
	s_lshl_b32 s10, s39, 1
	v_lshl_add_u64 v[34:35], v[32:33], 0, s[10:11]
	global_load_dwordx4 v[64:67], v[34:35], off offset:1024
	global_load_dwordx4 v[68:71], v[34:35], off offset:2048
	v_lshl_add_u64 v[34:35], v[32:33], 0, s[14:15]
	s_mov_b32 s31, s11
	s_mov_b32 s35, s11
	v_lshl_add_u64 v[36:37], v[34:35], 0, s[30:31]
	v_lshl_add_u64 v[34:35], v[34:35], 0, s[34:35]
	global_load_dwordx4 v[72:75], v[36:37], off
	global_load_dwordx4 v[76:79], v[34:35], off
	v_lshl_add_u64 v[34:35], v[32:33], 0, s[16:17]
	v_lshl_add_u64 v[36:37], v[34:35], 0, s[30:31]
	v_lshl_add_u64 v[34:35], v[34:35], 0, s[34:35]
	v_lshl_add_u64 v[32:33], v[32:33], 0, s[20:21]
	global_load_dwordx4 v[80:83], v[36:37], off
	global_load_dwordx4 v[84:87], v[34:35], off
	v_lshl_add_u64 v[34:35], v[32:33], 0, s[30:31]
	v_lshl_add_u64 v[32:33], v[32:33], 0, s[34:35]
	global_load_dwordx4 v[88:91], v[34:35], off
	global_load_dwordx4 v[92:95], v[32:33], off
; #define LDS_AS __attribute__((address_space(3)))
; template <int MODE>
; DI void attn_subtile(LDS_AS const char* Kl, LDS_AS const char* Vl, LDS_AS const char* biasl, const bf16x8 (&q)[4], AttnState& st, int kpos0, int qpos, bool need_mask, int lane) {
;     ...
;         f32x16 lk;
; #pragma unroll
;         for (int i = 0; i < 16; ++i) {
;             const float z = s[i];
;             const float e = __builtin_amdgcn_exp2f(-fabsf(z));
;             const float sp = __builtin_amdgcn_logf(1.0f + e);
;             float lkv = -fmaxf(z, 0.f) - sp;
;             float lsv = z + lkv;
;             if (need_mask && (kpos0 + crow(i, hh) >= qpos)) { lkv = 0.f; lsv = -INFINITY; }
;             lk[i] = lkv; s[i] = lsv;
;         }
;         float tot[4], suf1[4], suf0[4];
; #pragma unroll
;         for (int g = 0; g < 4; ++g) { suf1[g] = lk[4 * g + 3] + lk[4 * g + 2]; suf0[g] = suf1[g] + lk[4 * g + 1]; tot[g] = suf0[g] + lk[4 * g]; }
;         float pb[4], cs[4];
; #pragma unroll
;         for (int g = 0; g < 4; ++g) { pb[g] = __shfl_xor(tot[g], 32); cs[g] = tot[g] + pb[g]; }
;         const float S3 = 0.f, S2 = cs[3], S1 = S2 + cs[2], S0 = S1 + cs[1], total = S0 + cs[0];
;         const float Sg[4] = {S0, S1, S2, S3};
; #pragma unroll
;         for (int g = 0; g < 4; ++g) {
;             const float base = st.l + Sg[g] + (hh == 0 ? pb[g] : 0.f);
;             s[4 * g + 3] = __builtin_amdgcn_exp2f(s[4 * g + 3] + base);
;             s[4 * g + 2] = __builtin_amdgcn_exp2f(s[4 * g + 2] + (base + lk[4 * g + 3]));
;             s[4 * g + 1] = __builtin_amdgcn_exp2f(s[4 * g + 1] + (base + suf1[g]));
;             s[4 * g + 0] = __builtin_amdgcn_exp2f(s[4 * g + 0] + (base + suf0[g]));
;         }
;         st.l += total;
;     }
;     bf16x8 pf[2];
; #pragma unroll
;     for (int s2 = 0; s2 < 2; ++s2) {
;         u32x4 w;
;         w[0] = pk2(s[8 * s2 + 0], s[8 * s2 + 1]); w[1] = pk2(s[8 * s2 + 2], s[8 * s2 + 3]);
;         w[2] = pk2(s[8 * s2 + 4], s[8 * s2 + 5]); w[3] = pk2(s[8 * s2 + 6], s[8 * s2 + 7]);
;         pf[s2] = __builtin_bit_cast(bf16x8, w);
;     }
;     const int i16 = lane & 15, qq = i16 >> 2, pp = i16 & 3, gg = (lane >> 4) & 1;
; #pragma unroll
;     for (int s2 = 0; s2 < 2; ++s2)
; #pragma unroll
;         for (int dt = 0; dt < 2; ++dt) {
;             LDS_AS const char* a_lo = Vl + (16 * s2 + 4 * hh + qq) * 144 + (32 * dt + 16 * gg + 4 * pp) * 2;
.Lsbl_430:
	s_or_b64 exec, exec, s[4:5]
	s_waitcnt lgkmcnt(0)
	ds_read_b128 v[32:35], v108
	ds_read_b128 v[112:115], v108 offset:32
	s_waitcnt lgkmcnt(1)
	v_mfma_f32_32x32x16_bf16 v[32:47], v[32:35], v[48:51], 0
	s_waitcnt lgkmcnt(0)
	v_mfma_f32_32x32x16_bf16 v[32:47], v[112:115], v[52:55], v[32:47]
	ds_read_b128 v[112:115], v108 offset:64
	ds_read_b128 v[116:119], v108 offset:96
	s_waitcnt lgkmcnt(1)
	v_mfma_f32_32x32x16_bf16 v[32:47], v[112:115], v[56:59], v[32:47]
	s_waitcnt lgkmcnt(0)
	v_mfma_f32_32x32x16_bf16 v[32:47], v[116:119], v[60:63], v[32:47]
	v_xor_b32_e32 v124, 32, v174
	v_lshlrev_b32_e32 v124, 2, v124
	ds_read_b64_tr_b16 v[208:209], v109 offset:4608
	ds_read_b64_tr_b16 v[210:211], v109 offset:5760
	ds_read_b64_tr_b16 v[212:213], v109 offset:4672
	ds_read_b64_tr_b16 v[214:215], v109 offset:5824
	ds_read_b64_tr_b16 v[216:217], v109 offset:6912
	ds_read_b64_tr_b16 v[218:219], v109 offset:8064
	ds_read_b64_tr_b16 v[220:221], v109 offset:6976
	ds_read_b64_tr_b16 v[222:223], v109 offset:8128
	s_nop 11
	v_exp_f32_e64 v176, -|v32|
	v_exp_f32_e64 v177, -|v33|
	v_exp_f32_e64 v178, -|v34|
	v_exp_f32_e64 v179, -|v35|
	v_exp_f32_e64 v180, -|v36|
	v_exp_f32_e64 v181, -|v37|
	v_exp_f32_e64 v182, -|v38|
	v_exp_f32_e64 v183, -|v39|
	v_add_f32_e32 v176, 1.0, v176
	v_add_f32_e32 v177, 1.0, v177
	v_add_f32_e32 v178, 1.0, v178
	v_add_f32_e32 v179, 1.0, v179
	v_add_f32_e32 v180, 1.0, v180
	v_add_f32_e32 v181, 1.0, v181
	v_add_f32_e32 v182, 1.0, v182
	v_add_f32_e32 v183, 1.0, v183
	v_log_f32_e32 v176, v176
	v_max_f32_e32 v192, 0, v32
	v_log_f32_e32 v177, v177
	v_max_f32_e32 v193, 0, v33
	v_log_f32_e32 v178, v178
	v_max_f32_e32 v194, 0, v34
	v_log_f32_e32 v179, v179
	v_max_f32_e32 v195, 0, v35
	v_log_f32_e32 v180, v180
	v_max_f32_e32 v196, 0, v36
	v_log_f32_e32 v181, v181
	v_max_f32_e32 v197, 0, v37
	v_log_f32_e32 v182, v182
	v_max_f32_e32 v198, 0, v38
	v_log_f32_e32 v183, v183
	v_max_f32_e32 v199, 0, v39
	v_sub_f32_e64 v176, -v192, v176
	v_sub_f32_e64 v177, -v193, v177
	v_sub_f32_e64 v178, -v194, v178
	v_sub_f32_e64 v179, -v195, v179
	v_sub_f32_e64 v180, -v196, v180
	v_sub_f32_e64 v181, -v197, v181
	v_sub_f32_e64 v182, -v198, v182
	v_sub_f32_e64 v183, -v199, v183
	v_add_f32_e32 v224, v179, v178
	v_add_f32_e32 v225, v183, v182
	v_add_f32_e32 v32, v32, v176
	v_add_f32_e32 v33, v33, v177
	v_add_f32_e32 v34, v34, v178
	v_add_f32_e32 v35, v35, v179
	v_add_f32_e32 v228, v224, v177
	v_add_f32_e32 v229, v225, v181
	v_add_f32_e32 v36, v36, v180
	v_add_f32_e32 v37, v37, v181
	v_add_f32_e32 v38, v38, v182
	v_add_f32_e32 v39, v39, v183
	v_add_f32_e32 v232, v228, v176
	v_add_f32_e32 v233, v229, v180
	v_exp_f32_e64 v184, -|v40|
	v_exp_f32_e64 v185, -|v41|
	v_exp_f32_e64 v186, -|v42|
	v_exp_f32_e64 v187, -|v43|
	v_exp_f32_e64 v188, -|v44|
	v_exp_f32_e64 v189, -|v45|
	v_exp_f32_e64 v190, -|v46|
	v_exp_f32_e64 v191, -|v47|
	v_add_f32_e32 v184, 1.0, v184
	v_add_f32_e32 v185, 1.0, v185
	v_add_f32_e32 v186, 1.0, v186
	v_add_f32_e32 v187, 1.0, v187
	v_add_f32_e32 v188, 1.0, v188
	v_add_f32_e32 v189, 1.0, v189
	v_add_f32_e32 v190, 1.0, v190
	v_add_f32_e32 v191, 1.0, v191
	v_log_f32_e32 v184, v184
	v_max_f32_e32 v200, 0, v40
	v_log_f32_e32 v185, v185
	v_max_f32_e32 v201, 0, v41
	v_log_f32_e32 v186, v186
	v_max_f32_e32 v202, 0, v42
	v_log_f32_e32 v187, v187
	v_max_f32_e32 v203, 0, v43
	v_log_f32_e32 v188, v188
	v_max_f32_e32 v204, 0, v44
	v_log_f32_e32 v189, v189
	v_max_f32_e32 v205, 0, v45
	v_log_f32_e32 v190, v190
	v_max_f32_e32 v206, 0, v46
	v_log_f32_e32 v191, v191
	v_max_f32_e32 v207, 0, v47
	v_sub_f32_e64 v184, -v200, v184
	v_sub_f32_e64 v185, -v201, v185
	v_sub_f32_e64 v186, -v202, v186
	v_sub_f32_e64 v187, -v203, v187
	v_sub_f32_e64 v188, -v204, v188
	v_sub_f32_e64 v189, -v205, v189
	v_sub_f32_e64 v190, -v206, v190
	v_sub_f32_e64 v191, -v207, v191
	v_add_f32_e32 v226, v187, v186
	v_add_f32_e32 v227, v191, v190
	v_add_f32_e32 v40, v40, v184
	v_add_f32_e32 v41, v41, v185
	v_add_f32_e32 v42, v42, v186
	v_add_f32_e32 v43, v43, v187
	v_add_f32_e32 v230, v226, v185
	v_add_f32_e32 v231, v227, v189
	v_add_f32_e32 v44, v44, v188
	v_add_f32_e32 v45, v45, v189
	v_add_f32_e32 v46, v46, v190
	v_add_f32_e32 v47, v47, v191
	v_add_f32_e32 v234, v230, v184
	v_add_f32_e32 v235, v231, v188
	ds_bpermute_b32 v238, v124, v234
	ds_bpermute_b32 v239, v124, v235
	ds_bpermute_b32 v237, v124, v233
	ds_bpermute_b32 v236, v124, v232
	s_waitcnt lgkmcnt(3)
	v_add_f32_e32 v240, v234, v238
	s_waitcnt lgkmcnt(2)
	v_add_f32_e32 v241, v235, v239
	v_cndmask_b32_e32 v245, 0, v239, vcc
	v_add_f32_e32 v245, v106, v245
	v_add_f32_e32 v120, v245, v191
	v_add_f32_e32 v121, v245, v227
	v_add_f32_e32 v122, v245, v231
	v_add_f32_e32 v47, v47, v245
	v_add_f32_e32 v46, v46, v120
	v_add_f32_e32 v45, v45, v121
	v_add_f32_e32 v44, v44, v122
	v_exp_f32_e32 v47, v47
	v_exp_f32_e32 v46, v46
	v_exp_f32_e32 v45, v45
	v_exp_f32_e32 v44, v44
	v_add_f32_e32 v243, v241, v240
	v_add_f32_e32 v245, v106, v241
	v_cndmask_b32_e32 v123, 0, v238, vcc
	v_add_f32_e32 v245, v123, v245
	v_add_f32_e32 v120, v245, v187
	v_add_f32_e32 v121, v245, v226
	v_add_f32_e32 v122, v245, v230
	v_add_f32_e32 v43, v43, v245
	v_add_f32_e32 v42, v42, v120
	v_add_f32_e32 v41, v41, v121
	v_add_f32_e32 v40, v40, v122
	v_exp_f32_e32 v43, v43
	v_exp_f32_e32 v42, v42
	v_exp_f32_e32 v41, v41
	v_exp_f32_e32 v40, v40
	v_cvt_pk_bf16_f32 v117, v42, v43
	v_cvt_pk_bf16_f32 v118, v44, v45
	v_cvt_pk_bf16_f32 v119, v46, v47
	v_cvt_pk_bf16_f32 v116, v40, v41
	s_waitcnt lgkmcnt(1)
	v_add_f32_e32 v242, v233, v237
	v_add_f32_e32 v244, v242, v243
	v_mfma_f32_32x32x16_bf16 v[16:31], v[216:219], v[116:119], v[16:31]
	v_add_f32_e32 v245, v106, v243
	v_cndmask_b32_e32 v123, 0, v237, vcc
	v_add_f32_e32 v245, v123, v245
	v_mfma_f32_32x32x16_bf16 v[0:15], v[220:223], v[116:119], v[0:15]
	v_add_f32_e32 v120, v245, v183
	v_add_f32_e32 v121, v245, v225
	v_add_f32_e32 v122, v245, v229
	v_add_f32_e32 v39, v39, v245
	v_add_f32_e32 v38, v38, v120
	v_add_f32_e32 v37, v37, v121
	v_add_f32_e32 v36, v36, v122
	v_exp_f32_e32 v39, v39
	v_exp_f32_e32 v38, v38
	v_exp_f32_e32 v37, v37
	v_exp_f32_e32 v36, v36
	s_waitcnt lgkmcnt(0)
	v_add_f32_e32 v245, v106, v244
	v_cndmask_b32_e32 v123, 0, v236, vcc
	v_add_f32_e32 v245, v123, v245
	v_add_f32_e32 v120, v245, v179
	v_add_f32_e32 v121, v245, v224
	v_add_f32_e32 v122, v245, v228
	v_add_f32_e32 v35, v35, v245
	v_add_f32_e32 v34, v34, v120
	v_add_f32_e32 v33, v33, v121
	v_add_f32_e32 v32, v32, v122
	v_exp_f32_e32 v35, v35
	v_exp_f32_e32 v34, v34
	v_exp_f32_e32 v33, v33
	v_exp_f32_e32 v32, v32
	v_cvt_pk_bf16_f32 v113, v34, v35
	v_cvt_pk_bf16_f32 v114, v36, v37
	v_cvt_pk_bf16_f32 v115, v38, v39
	v_cvt_pk_bf16_f32 v112, v32, v33
	v_cmp_lt_i32_e64 s[0:1], 31, v110
	s_mov_b64 s[4:5], -1
	s_nop 0
	v_mfma_f32_32x32x16_bf16 v[16:31], v[208:211], v[112:115], v[16:31]
	v_mfma_f32_32x32x16_bf16 v[0:15], v[212:215], v[112:115], v[0:15]
	s_and_saveexec_b64 s[36:37], s[0:1]
	s_cbranch_execz .LBB0_427
; template <int MODE>
; DI void attn_subtile(LDS_AS const char* Kl, LDS_AS const char* Vl, LDS_AS const char* biasl, const bf16x8 (&q)[4], AttnState& st, int kpos0, int qpos, bool need_mask, int lane) {
;     ...
;         st.l += total;
; DI void prompt_sb_unit(const Params& p, int b, int h, int qt, char* smem) {
;     ...
;             if (kn < 0 || __all(st.l < -SB_THRESH)) break;
;             kp = kn;
	v_add_f32_e32 v32, v232, v236
	v_add_f32_e32 v32, v32, v244
	v_add_f32_e32 v106, v106, v32
	v_cmp_gt_f32_e64 s[0:1], s90, v106
	s_cmp_eq_u64 s[0:1], exec
	s_cselect_b64 s[0:1], -1, 0
	s_sub_i32 s42, s42, 32
	s_orn2_b64 s[4:5], s[0:1], exec
	s_branch .LBB0_427

; #define LDS_AS __attribute__((address_space(3)))
; DI void prompt_sb_unit(const Params& p, int b, int h, int qt, char* smem) {
;     ...
;         for (;;) {
;             asm volatile("s_waitcnt lgkmcnt(0)" ::: "memory");
; #pragma unroll
;             for (int i = 0; i < 4; ++i) { *(LDS_AS u32x4*)(lb + (r0 + 8 * i) * 144 + c0 * 16) = rk[i]; *(LDS_AS u32x4*)(lb + 4608 + (r0 + 8 * i) * 144 + c0 * 16) = rv[i]; }
;             const int kn = kp - 32;
;             if (kn >= 0) {
;                 const bf16_t* kb = ub + (size_t)kn * NU;
; #pragma unroll
;                 for (int i = 0; i < 4; ++i) { rk[i] = *(const u32x4*)(kb + (size_t)(8 * i) * NU + kcol); rv[i] = *(const u32x4*)(kb + (size_t)(8 * i) * NU + vcol); }
;             }
.LBB0_428:
	s_cmp_lg_u32 s42, 0
	s_cbranch_scc1 .Lsbl_body
	v_add_u32_e32 v32, s42, v104
	s_waitcnt lgkmcnt(0)
	v_add_u32_e32 v110, 0x1000, v32
	v_cmp_lt_i32_e64 s[0:1], 31, v110
	s_waitcnt vmcnt(7)
	ds_write_b128 v107, v[64:67]
	s_waitcnt vmcnt(6)
	ds_write_b128 v107, v[68:71] offset:4608
	s_waitcnt vmcnt(5)
	ds_write_b128 v107, v[72:75] offset:1152
	s_waitcnt vmcnt(4)
	ds_write_b128 v107, v[76:79] offset:5760
	s_waitcnt vmcnt(3)
	ds_write_b128 v107, v[80:83] offset:2304
	s_waitcnt vmcnt(2)
	ds_write_b128 v107, v[84:87] offset:6912
	s_waitcnt vmcnt(1)
	ds_write_b128 v107, v[88:91] offset:3456
	s_waitcnt vmcnt(0)
	ds_write_b128 v107, v[92:95] offset:8064
	s_and_saveexec_b64 s[4:5], s[0:1]
	s_cbranch_execz .LBB0_430
	v_add_u32_e32 v130, 0xfe0, v32
	v_lshlrev_b64 v[32:33], 13, v[130:131]
	v_lshl_add_u64 v[32:33], v[102:103], 0, v[32:33]
	s_lshl_b32 s10, s39, 1
	v_lshl_add_u64 v[34:35], v[32:33], 0, s[10:11]
	global_load_dwordx4 v[64:67], v[34:35], off offset:1024
	global_load_dwordx4 v[68:71], v[34:35], off offset:2048
	v_lshl_add_u64 v[34:35], v[32:33], 0, s[14:15]
	s_mov_b32 s31, s11
	s_mov_b32 s35, s11
	v_lshl_add_u64 v[36:37], v[34:35], 0, s[30:31]
	v_lshl_add_u64 v[34:35], v[34:35], 0, s[34:35]
	global_load_dwordx4 v[72:75], v[36:37], off
	global_load_dwordx4 v[76:79], v[34:35], off
	v_lshl_add_u64 v[34:35], v[32:33], 0, s[16:17]
	v_lshl_add_u64 v[36:37], v[34:35], 0, s[30:31]
	v_lshl_add_u64 v[34:35], v[34:35], 0, s[34:35]
	v_lshl_add_u64 v[32:33], v[32:33], 0, s[20:21]
	global_load_dwordx4 v[80:83], v[36:37], off
	global_load_dwordx4 v[84:87], v[34:35], off
	v_lshl_add_u64 v[34:35], v[32:33], 0, s[30:31]
	v_lshl_add_u64 v[32:33], v[32:33], 0, s[34:35]
	global_load_dwordx4 v[88:91], v[34:35], off
	global_load_dwordx4 v[92:95], v[32:33], off
